# scan: next-chunk U^T loaded as 2 coalesced 16-B loads per lane + permlane16/32 swap lane exchange instead of 4 x 8-B loads
# speedup vs baseline: 1.0410x; 1.0023x over previous
.LBB0_1090:
	v_mov_b32_e32 v40, v125
	s_add_i32 s64, s19, 1
	s_cmp_ge_u32 s64, s22
	v_and_b32_e32 v135, 15, v40
	v_ashrrev_i32_e32 v136, 4, v40
	s_cbranch_scc1 .LBB0_1092
	s_add_i32 s20, s63, s19
	s_ashr_i32 s21, s20, 31
	s_lshl_b64 s[58:59], s[20:21], 2
	s_add_u32 s58, s24, s58
	s_addc_u32 s59, s25, s59
	s_mul_hi_i32 s21, s20, 0x16000
	s_mul_i32 s20, s20, 0x16000
	v_lshlrev_b32_e32 v41, 4, v40
	s_add_u32 s20, s31, s20
	v_add_u32_e32 v42, s35, v41
	s_addc_u32 s21, s34, s21
	v_lshrrev_b32_e32 v43, 8, v42
	global_load_dword v134, v173, s[58:59]
	s_add_u32 s58, s20, 0x8000
	v_xor_b32_e32 v43, v43, v40
	s_addc_u32 s59, s21, 0
	v_lshlrev_b32_e32 v43, 4, v43
	v_and_b32_e32 v42, 0xffffff00, v42
	s_bitcmp1_b32 s64, 0
	v_and_or_b32 v172, v43, s69, v42
	s_cselect_b32 s65, 0xe000, 0
	v_lshl_add_u64 v[42:43], s[58:59], 0, v[172:173]
	s_add_i32 s65, s36, s65
	s_mov_b32 m0, s65
	s_nop 0
	global_load_lds_dwordx4 v[42:43], off
	v_add_u32_e32 v42, s37, v41
	v_lshrrev_b32_e32 v43, 8, v42
	v_xor_b32_e32 v43, v43, v40
	v_lshlrev_b32_e32 v43, 4, v43
	v_and_b32_e32 v42, 0xffffff00, v42
	v_and_or_b32 v172, v43, s69, v42
	v_lshl_add_u64 v[42:43], s[58:59], 0, v[172:173]
	s_add_i32 s66, s65, 0x2000
	s_mov_b32 m0, s66
	s_nop 0
	global_load_lds_dwordx4 v[42:43], off
	v_add_u32_e32 v42, s39, v41
	v_lshrrev_b32_e32 v43, 8, v42
	v_xor_b32_e32 v43, v43, v40
	v_lshlrev_b32_e32 v43, 4, v43
	v_and_b32_e32 v42, 0xffffff00, v42
	v_and_or_b32 v172, v43, s69, v42
	v_lshl_add_u64 v[42:43], s[58:59], 0, v[172:173]
	s_add_i32 s66, s65, 0x4000
	s_mov_b32 m0, s66
	s_nop 0
	global_load_lds_dwordx4 v[42:43], off
	v_add_u32_e32 v42, s41, v41
	v_lshrrev_b32_e32 v43, 8, v42
	v_xor_b32_e32 v43, v43, v40
	v_lshlrev_b32_e32 v43, 4, v43
	v_and_b32_e32 v42, 0xffffff00, v42
	v_and_or_b32 v172, v43, s69, v42
	v_lshl_add_u64 v[42:43], s[58:59], 0, v[172:173]
	s_add_i32 s66, s65, 0x6000
	s_mov_b32 m0, s66
	s_nop 0
	global_load_lds_dwordx4 v[42:43], off
	v_add_u32_e32 v42, s45, v41
	v_lshrrev_b32_e32 v43, 8, v42
	v_xor_b32_e32 v43, v43, v40
	v_lshlrev_b32_e32 v43, 4, v43
	v_and_b32_e32 v42, 0xffffff80, v42
	v_and_or_b32 v172, v43, s93, v42
	v_lshl_add_u64 v[42:43], s[58:59], 0, v[172:173]
	s_add_i32 s66, s65, 0x8000
	s_mov_b32 m0, s66
	s_nop 0
	global_load_lds_dwordx4 v[42:43], off
	v_add_u32_e32 v42, s47, v41
	v_lshrrev_b32_e32 v43, 8, v42
	v_xor_b32_e32 v43, v43, v40
	v_lshlrev_b32_e32 v43, 4, v43
	v_and_b32_e32 v42, 0xffffff80, v42
	v_and_or_b32 v172, v43, s93, v42
	v_lshl_add_u64 v[42:43], s[58:59], 0, v[172:173]
	v_add_u32_e32 v41, s49, v41
	s_add_i32 s66, s65, 0xa000
	s_mov_b32 m0, s66
	s_nop 0
	global_load_lds_dwordx4 v[42:43], off
	v_lshrrev_b32_e32 v42, 8, v41
	v_xor_b32_e32 v42, v42, v40
	v_lshlrev_b32_e32 v42, 4, v42
	v_and_b32_e32 v41, 0xffffff80, v41
	v_and_or_b32 v172, v42, s93, v41
	v_lshl_add_u64 v[42:43], s[58:59], 0, v[172:173]
	s_add_i32 s65, s65, 0xc000
	s_mov_b32 m0, s65
	s_nop 0
	global_load_lds_dwordx4 v[42:43], off
	v_or_b32_e32 v41, s28, v135
	v_lshlrev_b32_e32 v42, 3, v136
	v_lshl_add_u32 v172, v41, 6, v42
	v_lshl_add_u64 v[42:43], v[172:173], 1, s[20:21]
	global_load_dwordx4 v[126:129], v[42:43], off
	global_load_dwordx4 v[130:133], v[42:43], off offset:64
.LBB0_1092:
	v_lshlrev_b32_e32 v146, 16, v32
	v_and_b32_e32 v147, 0xffff0000, v32
	v_lshlrev_b32_e32 v148, 16, v33
	v_and_b32_e32 v149, 0xffff0000, v33
	v_xor_b32_e32 v32, 0x80000000, v1
	v_xor_b32_e32 v33, 0x80000000, v0
	v_cvt_pk_bf16_f32 v150, v33, v32
	v_xor_b32_e32 v32, 0x80000000, v2
	v_xor_b32_e32 v33, 0x80000000, v3
	v_cvt_pk_bf16_f32 v151, v32, v33
	v_xor_b32_e32 v32, 0x80000000, v4
	v_xor_b32_e32 v33, 0x80000000, v5
	v_cvt_pk_bf16_f32 v152, v32, v33
	v_xor_b32_e32 v32, 0x80000000, v6
	v_xor_b32_e32 v33, 0x80000000, v7
	v_cvt_pk_bf16_f32 v153, v32, v33
	v_xor_b32_e32 v32, 0x80000000, v8
	v_xor_b32_e32 v33, 0x80000000, v9
	v_cvt_pk_bf16_f32 v154, v32, v33
	v_xor_b32_e32 v32, 0x80000000, v10
	v_xor_b32_e32 v33, 0x80000000, v11
	v_cvt_pk_bf16_f32 v155, v32, v33
	v_xor_b32_e32 v32, 0x80000000, v12
	v_xor_b32_e32 v33, 0x80000000, v13
	v_cvt_pk_bf16_f32 v156, v32, v33
	v_xor_b32_e32 v32, 0x80000000, v14
	v_xor_b32_e32 v33, 0x80000000, v15
	v_cvt_pk_bf16_f32 v157, v32, v33
	v_xor_b32_e32 v32, 0x80000000, v16
	v_xor_b32_e32 v33, 0x80000000, v17
	v_cvt_pk_bf16_f32 v158, v32, v33
	v_xor_b32_e32 v32, 0x80000000, v18
	v_xor_b32_e32 v33, 0x80000000, v19
	v_cvt_pk_bf16_f32 v159, v32, v33
	v_xor_b32_e32 v32, 0x80000000, v20
	v_xor_b32_e32 v33, 0x80000000, v21
	v_cvt_pk_bf16_f32 v160, v32, v33
	v_xor_b32_e32 v32, 0x80000000, v22
	v_xor_b32_e32 v33, 0x80000000, v23
	v_cvt_pk_bf16_f32 v161, v32, v33
	v_xor_b32_e32 v32, 0x80000000, v28
	v_xor_b32_e32 v33, 0x80000000, v29
	s_bitcmp1_b32 s19, 0
	v_cvt_pk_bf16_f32 v162, v32, v33
	v_xor_b32_e32 v32, 0x80000000, v30
	v_xor_b32_e32 v33, 0x80000000, v31
	s_cselect_b32 s19, 0xe000, 0
	v_cvt_pk_bf16_f32 v163, v32, v33
	v_xor_b32_e32 v32, 0x80000000, v24
	v_xor_b32_e32 v33, 0x80000000, v25
	s_add_i32 s19, s19, 0
	v_cvt_pk_bf16_f32 v164, v32, v33
	v_xor_b32_e32 v32, 0x80000000, v26
	v_xor_b32_e32 v33, 0x80000000, v27
	v_and_b32_e32 v43, -16, v40
	v_cvt_pk_bf16_f32 v165, v32, v33
	v_lshlrev_b32_e32 v32, 4, v135
	v_lshl_add_u32 v33, v135, 8, s19
	v_add_u32_e32 v170, 64, v43
	v_add_u32_e32 v172, 0x80, v43
	v_add_u32_e32 v186, 0xc0, v43
	v_xad_u32 v137, v32, v43, v33
	v_xad_u32 v171, v170, v32, v33
	v_xad_u32 v172, v172, v32, v33
	v_xad_u32 v210, v186, v32, v33
	v_lshlrev_b32_e32 v138, 16, v38
	v_and_b32_e32 v139, 0xffff0000, v38
	v_lshlrev_b32_e32 v140, 16, v39
	v_and_b32_e32 v141, 0xffff0000, v39
	v_lshlrev_b32_e32 v42, 3, v40
	ds_read_b128 v[38:41], v137
	ds_read_b128 v[166:169], v171
	ds_read_b128 v[182:185], v172
	ds_read_b128 v[186:189], v210
	ds_read_b128 v[190:193], v137 offset:4096
	ds_read_b128 v[194:197], v171 offset:4096
	ds_read_b128 v[198:201], v172 offset:4096
	ds_read_b128 v[202:205], v210 offset:4096
	v_lshlrev_b32_e32 v142, 16, v34
	v_and_b32_e32 v143, 0xffff0000, v34
	v_lshlrev_b32_e32 v144, 16, v35
	v_and_b32_e32 v145, 0xffff0000, v35
	v_lshlrev_b32_e32 v34, 16, v36
	v_and_b32_e32 v35, 0xffff0000, v36
	v_lshlrev_b32_e32 v36, 16, v37
	v_and_b32_e32 v37, 0xffff0000, v37
	s_waitcnt lgkmcnt(7)
	v_mfma_f32_16x16x32_bf16 v[38:41], v[38:41], v[150:153], v[138:141]
	s_waitcnt lgkmcnt(6)
	v_mfma_f32_16x16x32_bf16 v[38:41], v[166:169], v[154:157], v[38:41]
	s_waitcnt lgkmcnt(5)
	v_mfma_f32_16x16x32_bf16 v[38:41], v[182:185], v[158:161], v[38:41]
	s_waitcnt lgkmcnt(4)
	v_mfma_f32_16x16x32_bf16 v[38:41], v[186:189], v[162:165], v[38:41]
	ds_read_b128 v[138:141], v137 offset:8192
	ds_read_b128 v[166:169], v171 offset:8192
	ds_read_b128 v[182:185], v172 offset:8192
	ds_read_b128 v[186:189], v210 offset:8192
	s_waitcnt lgkmcnt(7)
	v_mfma_f32_16x16x32_bf16 v[142:145], v[190:193], v[150:153], v[142:145]
	s_waitcnt lgkmcnt(6)
	v_mfma_f32_16x16x32_bf16 v[142:145], v[194:197], v[154:157], v[142:145]
	s_waitcnt lgkmcnt(5)
	v_mfma_f32_16x16x32_bf16 v[142:145], v[198:201], v[158:161], v[142:145]
	s_waitcnt lgkmcnt(4)
	v_mfma_f32_16x16x32_bf16 v[142:145], v[202:205], v[162:165], v[142:145]
	ds_read_b128 v[190:193], v137 offset:12288
	ds_read_b128 v[194:197], v171 offset:12288
	ds_read_b128 v[198:201], v172 offset:12288
	ds_read_b128 v[202:205], v210 offset:12288
	s_waitcnt lgkmcnt(7)
	v_mfma_f32_16x16x32_bf16 v[32:35], v[138:141], v[150:153], v[34:37]
	s_waitcnt lgkmcnt(6)
	v_mfma_f32_16x16x32_bf16 v[32:35], v[166:169], v[154:157], v[32:35]
	s_waitcnt lgkmcnt(5)
	v_mfma_f32_16x16x32_bf16 v[32:35], v[182:185], v[158:161], v[32:35]
	s_waitcnt lgkmcnt(4)
	v_mfma_f32_16x16x32_bf16 v[32:35], v[186:189], v[162:165], v[32:35]
	ds_read_b128 v[138:141], v137 offset:16384
	ds_read_b128 v[166:169], v171 offset:16384
	ds_read_b128 v[182:185], v172 offset:16384
	ds_read_b128 v[186:189], v210 offset:16384
	s_waitcnt lgkmcnt(7)
	v_mfma_f32_16x16x32_bf16 v[146:149], v[190:193], v[150:153], v[146:149]
	s_waitcnt lgkmcnt(6)
	v_mfma_f32_16x16x32_bf16 v[146:149], v[194:197], v[154:157], v[146:149]
	s_waitcnt lgkmcnt(5)
	v_mfma_f32_16x16x32_bf16 v[146:149], v[198:201], v[158:161], v[146:149]
	s_waitcnt lgkmcnt(4)
	v_mfma_f32_16x16x32_bf16 v[146:149], v[202:205], v[162:165], v[146:149]
	ds_read_b128 v[190:193], v137 offset:20480
	ds_read_b128 v[194:197], v171 offset:20480
	ds_read_b128 v[198:201], v172 offset:20480
	ds_read_b128 v[202:205], v210 offset:20480
	v_xor_b32_e32 v153, 0x80008000, v153
	v_xor_b32_e32 v152, 0x80008000, v152
	v_xor_b32_e32 v151, 0x80008000, v151
	v_xor_b32_e32 v150, 0x80008000, v150
	v_xor_b32_e32 v157, 0x80008000, v157
	v_xor_b32_e32 v156, 0x80008000, v156
	s_waitcnt lgkmcnt(7)
	v_mfma_f32_16x16x32_bf16 v[138:141], v[138:141], v[150:153], 0
	v_xor_b32_e32 v155, 0x80008000, v155
	v_xor_b32_e32 v154, 0x80008000, v154
	v_xor_b32_e32 v161, 0x80008000, v161
	v_xor_b32_e32 v160, 0x80008000, v160
	s_waitcnt lgkmcnt(6)
	v_mfma_f32_16x16x32_bf16 v[138:141], v[166:169], v[154:157], v[138:141]
	v_xor_b32_e32 v159, 0x80008000, v159
	v_xor_b32_e32 v158, 0x80008000, v158
	v_xor_b32_e32 v165, 0x80008000, v165
	v_xor_b32_e32 v164, 0x80008000, v164
	s_waitcnt lgkmcnt(5)
	v_mfma_f32_16x16x32_bf16 v[138:141], v[182:185], v[158:161], v[138:141]
	v_xor_b32_e32 v163, 0x80008000, v163
	v_xor_b32_e32 v162, 0x80008000, v162
	s_waitcnt lgkmcnt(4)
	s_nop 0
	v_mfma_f32_16x16x32_bf16 v[138:141], v[186:189], v[162:165], v[138:141]
	ds_read_b128 v[166:169], v137 offset:24576
	ds_read_b128 v[182:185], v171 offset:24576
	ds_read_b128 v[186:189], v172 offset:24576
	ds_read_b128 v[206:209], v210 offset:24576
	s_waitcnt lgkmcnt(7)
	v_mfma_f32_16x16x32_bf16 v[190:193], v[190:193], v[150:153], 0
	s_waitcnt lgkmcnt(6)
	v_mfma_f32_16x16x32_bf16 v[190:193], v[194:197], v[154:157], v[190:193]
	s_waitcnt lgkmcnt(5)
	v_mfma_f32_16x16x32_bf16 v[190:193], v[198:201], v[158:161], v[190:193]
	s_waitcnt lgkmcnt(4)
	v_mfma_f32_16x16x32_bf16 v[190:193], v[202:205], v[162:165], v[190:193]
	ds_read_b128 v[194:197], v137 offset:28672
	ds_read_b128 v[198:201], v171 offset:28672
	ds_read_b128 v[202:205], v172 offset:28672
	ds_read_b128 v[210:213], v210 offset:28672
	s_waitcnt lgkmcnt(7)
	v_mfma_f32_16x16x32_bf16 v[166:169], v[166:169], v[150:153], 0
	v_and_b32_e32 v36, 0x70, v42
	v_lshl_add_u32 v37, v135, 7, s19
	v_xad_u32 v137, v36, v43, v37
	s_waitcnt lgkmcnt(6)
	v_mfma_f32_16x16x32_bf16 v[166:169], v[182:185], v[154:157], v[166:169]
	v_xad_u32 v170, v170, v36, v37
	ds_read_b128 v[182:185], v137 offset:49152
	s_waitcnt lgkmcnt(6)
	v_mfma_f32_16x16x32_bf16 v[166:169], v[186:189], v[158:161], v[166:169]
	s_waitcnt lgkmcnt(5)
	v_mfma_f32_16x16x32_bf16 v[166:169], v[206:209], v[162:165], v[166:169]
	ds_read_b128 v[186:189], v170 offset:49152
	ds_read_b128 v[206:209], v137 offset:51200
	ds_read_b128 v[230:233], v170 offset:51200
	s_waitcnt lgkmcnt(7)
	v_mfma_f32_16x16x32_bf16 v[150:153], v[194:197], v[150:153], 0
	s_waitcnt lgkmcnt(6)
	v_mfma_f32_16x16x32_bf16 v[150:153], v[198:201], v[154:157], v[150:153]
	s_waitcnt lgkmcnt(5)
	v_mfma_f32_16x16x32_bf16 v[150:153], v[202:205], v[158:161], v[150:153]
	ds_read_b128 v[154:157], v137 offset:53248
	ds_read_b128 v[158:161], v137 offset:55296
	ds_read_b128 v[194:197], v170 offset:53248
	ds_read_b128 v[198:201], v170 offset:55296
	s_waitcnt lgkmcnt(8)
	v_mfma_f32_16x16x32_bf16 v[150:153], v[210:213], v[162:165], v[150:153]
	v_cvt_pk_bf16_f32 v162, v38, v39
	v_cvt_pk_bf16_f32 v163, v40, v41
	v_cvt_pk_bf16_f32 v164, v142, v143
	v_cvt_pk_bf16_f32 v165, v144, v145
	v_cvt_pk_bf16_f32 v142, v32, v33
	v_cvt_pk_bf16_f32 v143, v34, v35
	s_waitcnt lgkmcnt(7)
	v_mfma_f32_16x16x32_bf16 v[36:39], v[182:185], v[162:165], v[138:141]
	v_cvt_pk_bf16_f32 v144, v146, v147
	v_cvt_pk_bf16_f32 v145, v148, v149
	s_waitcnt lgkmcnt(5)
	v_mfma_f32_16x16x32_bf16 v[32:35], v[206:209], v[162:165], v[190:193]
	v_mfma_f32_16x16x32_bf16 v[138:141], v[186:189], v[142:145], v[36:39]
	ds_read_b128 v[146:149], v137 offset:32768
	ds_read_b128 v[182:185], v137 offset:34816
	ds_read_b128 v[186:189], v170 offset:32768
	ds_read_b128 v[190:193], v170 offset:34816
	s_waitcnt lgkmcnt(8)
	v_mfma_f32_16x16x32_bf16 v[40:43], v[230:233], v[142:145], v[32:35]
	s_waitcnt lgkmcnt(7)
	v_mfma_f32_16x16x32_bf16 v[32:35], v[154:157], v[162:165], v[166:169]
	s_waitcnt lgkmcnt(5)
	v_mfma_f32_16x16x32_bf16 v[36:39], v[194:197], v[142:145], v[32:35]
	v_mfma_f32_16x16x32_bf16 v[32:35], v[158:161], v[162:165], v[150:153]
	s_nop 2
	ds_read_b128 v[150:153], v137 offset:36864
	ds_read_b128 v[154:157], v170 offset:36864
	ds_read_b128 v[158:161], v137 offset:38912
	ds_read_b128 v[166:169], v170 offset:38912
	s_waitcnt lgkmcnt(8)
	v_mfma_f32_16x16x32_bf16 v[32:35], v[198:201], v[142:145], v[32:35]
	v_mul_f32_e64 v2, v124, v2
	v_mul_f32_e64 v3, v124, v3
	v_pk_mul_f32 v[0:1], v[124:125], v[0:1] op_sel_hi:[0,1]
	v_pk_mul_f32 v[6:7], v[124:125], v[6:7] op_sel_hi:[0,1]
	v_pk_mul_f32 v[4:5], v[124:125], v[4:5] op_sel_hi:[0,1]
	s_waitcnt lgkmcnt(7)
	v_mfma_f32_16x16x32_bf16 v[0:3], v[146:149], v[162:165], v[0:3]
	s_waitcnt lgkmcnt(6)
	v_mfma_f32_16x16x32_bf16 v[4:7], v[182:185], v[162:165], v[4:7]
	s_waitcnt lgkmcnt(5)
	v_mfma_f32_16x16x32_bf16 v[0:3], v[186:189], v[142:145], v[0:3]
	s_waitcnt lgkmcnt(4)
	v_mfma_f32_16x16x32_bf16 v[4:7], v[190:193], v[142:145], v[4:7]
	ds_read_b128 v[146:149], v137 offset:40960
	ds_read_b128 v[182:185], v170 offset:40960
	ds_read_b128 v[186:189], v137 offset:43008
	ds_read_b128 v[190:193], v170 offset:43008
	v_pk_mul_f32 v[10:11], v[124:125], v[10:11] op_sel_hi:[0,1]
	v_pk_mul_f32 v[8:9], v[124:125], v[8:9] op_sel_hi:[0,1]
	v_pk_mul_f32 v[14:15], v[124:125], v[14:15] op_sel_hi:[0,1]
	v_pk_mul_f32 v[12:13], v[124:125], v[12:13] op_sel_hi:[0,1]
	s_waitcnt lgkmcnt(7)
	v_mfma_f32_16x16x32_bf16 v[8:11], v[150:153], v[162:165], v[8:11]
	s_waitcnt lgkmcnt(5)
	v_mfma_f32_16x16x32_bf16 v[12:15], v[158:161], v[162:165], v[12:15]
	v_mfma_f32_16x16x32_bf16 v[8:11], v[154:157], v[142:145], v[8:11]
	s_waitcnt lgkmcnt(4)
	v_mfma_f32_16x16x32_bf16 v[12:15], v[166:169], v[142:145], v[12:15]
	ds_read_b128 v[150:153], v137 offset:45056
	ds_read_b128 v[154:157], v170 offset:45056
	ds_read_b128 v[158:161], v137 offset:47104
	ds_read_b128 v[166:169], v170 offset:47104
	v_pk_mul_f32 v[18:19], v[124:125], v[18:19] op_sel_hi:[0,1]
	v_pk_mul_f32 v[16:17], v[124:125], v[16:17] op_sel_hi:[0,1]
	v_pk_mul_f32 v[22:23], v[124:125], v[22:23] op_sel_hi:[0,1]
	v_pk_mul_f32 v[20:21], v[124:125], v[20:21] op_sel_hi:[0,1]
	s_waitcnt lgkmcnt(7)
	v_mfma_f32_16x16x32_bf16 v[16:19], v[146:149], v[162:165], v[16:19]
	s_waitcnt lgkmcnt(5)
	v_mfma_f32_16x16x32_bf16 v[20:23], v[186:189], v[162:165], v[20:23]
	v_mfma_f32_16x16x32_bf16 v[16:19], v[182:185], v[142:145], v[16:19]
	s_waitcnt lgkmcnt(4)
	v_mfma_f32_16x16x32_bf16 v[20:23], v[190:193], v[142:145], v[20:23]
	s_ashr_i32 s19, s18, 31
	s_lshl_b64 s[20:21], s[18:19], 11
	v_pk_mul_f32 v[30:31], v[124:125], v[30:31] op_sel_hi:[0,1]
	v_pk_mul_f32 v[28:29], v[124:125], v[28:29] op_sel_hi:[0,1]
	v_pk_mul_f32 v[26:27], v[124:125], v[26:27] op_sel_hi:[0,1]
	v_pk_mul_f32 v[24:25], v[124:125], v[24:25] op_sel_hi:[0,1]
	s_add_u32 s20, s23, s20
	s_addc_u32 s21, s62, s21
	s_waitcnt lgkmcnt(3)
	v_mfma_f32_16x16x32_bf16 v[28:31], v[150:153], v[162:165], v[28:31]
	s_andn2_b64 vcc, exec, s[12:13]
	s_waitcnt lgkmcnt(1)
	v_mfma_f32_16x16x32_bf16 v[24:27], v[158:161], v[162:165], v[24:27]
	v_mfma_f32_16x16x32_bf16 v[28:31], v[154:157], v[142:145], v[28:31]
	s_waitcnt lgkmcnt(0)
	v_mfma_f32_16x16x32_bf16 v[24:27], v[166:169], v[142:145], v[24:27]
	s_cbranch_vccnz .Lscan_smp
	s_bitcmp1_b32 s64, 0
	s_mov_b32 s65, 0x20010
	s_cselect_b32 s65, 0x1c000, s65
	v_lshlrev_b32_e32 v137, 10, v136
	s_lshl_b32 s66, s28, 1
	v_lshl_add_u32 v137, v135, 1, v137
	s_add_i32 s66, s66, s65
	v_lshlrev_b32_e32 v171, 11, v136
	v_add_u32_e32 v137, s66, v137
	v_lshl_add_u32 v171, v135, 4, v171
	v_cvt_pk_bf16_f32 v124, v138, v138
	ds_write_b16 v137, v124
	v_cvt_pk_bf16_f32 v124, v139, v139
	ds_write_b16 v137, v124 offset:256
	v_cvt_pk_bf16_f32 v124, v140, v140
	ds_write_b16 v137, v124 offset:512
	v_cvt_pk_bf16_f32 v124, v141, v141
	ds_write_b16 v137, v124 offset:768
	v_cvt_pk_bf16_f32 v124, v40, v40
	ds_write_b16 v137, v124 offset:4096
	v_cvt_pk_bf16_f32 v124, v41, v41
	ds_write_b16 v137, v124 offset:4352
	v_cvt_pk_bf16_f32 v124, v42, v42
	ds_write_b16 v137, v124 offset:4608
	v_cvt_pk_bf16_f32 v124, v43, v43
	ds_write_b16 v137, v124 offset:4864
	v_cvt_pk_bf16_f32 v124, v36, v36
	ds_write_b16 v137, v124 offset:8192
	v_cvt_pk_bf16_f32 v124, v37, v37
	ds_write_b16 v137, v124 offset:8448
	v_cvt_pk_bf16_f32 v124, v38, v38
	ds_write_b16 v137, v124 offset:8704
	v_cvt_pk_bf16_f32 v124, v39, v39
	ds_write_b16 v137, v124 offset:8960
	v_cvt_pk_bf16_f32 v124, v32, v32
	ds_write_b16 v137, v124 offset:12288
	v_cvt_pk_bf16_f32 v124, v33, v33
	ds_write_b16 v137, v124 offset:12544
	v_cvt_pk_bf16_f32 v124, v34, v34
	ds_write_b16 v137, v124 offset:12800
	v_cvt_pk_bf16_f32 v124, v35, v35
	ds_write_b16 v137, v124 offset:13056
	s_lshl_b32 s66, s28, 6
	s_add_i32 s66, s66, s65
	v_lshl_add_u32 v170, v125, 4, s66
	s_lshl_b32 s66, s28, 9
	v_add_u32_e32 v171, s66, v171
	s_add_u32 s58, s20, 0x10000
	s_addc_u32 s59, s21, 0
	s_add_i32 s18, s18, 64
	s_waitcnt vmcnt(0) lgkmcnt(0)
	s_barrier
	ds_read_b128 v[146:149], v170
	ds_read_b128 v[150:153], v170 offset:8192
	v_permlane16_swap_b32_e32 v126, v128
	v_permlane16_swap_b32_e32 v127, v129
	v_permlane16_swap_b32_e32 v130, v132
	v_permlane16_swap_b32_e32 v131, v133
	s_nop 1
	v_permlane32_swap_b32_e32 v126, v128
	v_permlane32_swap_b32_e32 v127, v129
	v_permlane32_swap_b32_e32 v130, v132
	v_permlane32_swap_b32_e32 v131, v133
	s_nop 1
	v_mov_b64_e32 v[38:39], v[126:127]
	v_mov_b64_e32 v[34:35], v[128:129]
	v_mov_b64_e32 v[36:37], v[130:131]
	v_mov_b64_e32 v[32:33], v[132:133]
	v_mov_b32_e32 v124, v134
	s_cmp_eq_u32 s22, s64
	s_mov_b32 s19, s64
	s_waitcnt lgkmcnt(1)
	global_store_dwordx4 v171, v[146:149], s[20:21]
	s_waitcnt lgkmcnt(0)
	global_store_dwordx4 v171, v[150:153], s[58:59]
	s_cbranch_scc1 .LBB0_1083
	s_branch .LBB0_1090
